# MLP1 tile remap variant: 8 m-tiles x 4 n-tiles per XCD per round
# speedup vs baseline: 1.0051x; 1.0051x over previous
.LBB0_1602:
	s_and_b32 s0, s35, 3
	s_lshl_b32 s0, s0, 2
	s_bfe_u32 s6, s35, 0x20003
	s_or_b32 s6, s6, s0
	s_bfe_u32 s0, s35, 0x30005
	s_bfe_u32 s1, s35, 0x10002
	s_lshl_b32 s1, s1, 3
	s_or_b32 s0, s0, s1
	s_lshr_b32 s1, s35, 8
	s_lshl_b32 s1, s1, 4
	s_or_b32 s0, s0, s1
	s_lshl_b32 s4, s0, 8
	s_ashr_i32 s5, s4, 31
	s_ashr_i32 s7, s6, 31
	s_lshl_b64 s[0:1], s[6:7], 19
	s_lshl_b64 s[8:9], s[4:5], 11
	v_readlane_b32 s10, v250, 44
	v_readlane_b32 s11, v250, 45
	s_add_u32 s10, s10, s8
	v_mov_b32_e32 v34, v172
	s_addc_u32 s11, s11, s9
	s_add_u32 s12, s31, s0
	v_lshlrev_b32_e32 v0, 4, v34
	v_ashrrev_i32_e32 v35, 3, v34
	v_and_b32_e32 v0, 0x70, v0
	s_addc_u32 s13, s34, s1
	v_lshl_or_b32 v0, v35, 11, v0
	v_lshl_add_u64 v[26:27], s[12:13], 0, v[0:1]
	v_add_co_u32_e32 v10, vcc, s52, v26
	v_lshl_add_u64 v[28:29], s[10:11], 0, v[0:1]
	s_nop 0
	v_addc_co_u32_e32 v11, vcc, 0, v27, vcc
	v_add_co_u32_e32 v14, vcc, s52, v28
	global_load_dwordx4 v[2:5], v0, s[12:13]
	global_load_dwordx4 v[6:9], v0, s[10:11]
	v_addc_co_u32_e32 v15, vcc, 0, v29, vcc
	v_add_co_u32_e32 v18, vcc, s56, v26
	global_load_dwordx4 v[10:13], v[10:11], off
	s_nop 0
	global_load_dwordx4 v[14:17], v[14:15], off
	v_addc_co_u32_e32 v19, vcc, 0, v27, vcc
	v_add_co_u32_e32 v22, vcc, s56, v28
	v_lshrrev_b32_e32 v36, 1, v35
	s_nop 0
	v_addc_co_u32_e32 v23, vcc, 0, v29, vcc
	v_add_co_u32_e32 v26, vcc, s57, v26
	global_load_dwordx4 v[18:21], v[18:19], off
	s_nop 0
	global_load_dwordx4 v[22:25], v[22:23], off
	v_addc_co_u32_e32 v27, vcc, 0, v27, vcc
	v_add_co_u32_e32 v30, vcc, s57, v28
	v_xor_b32_e32 v34, v36, v34
	s_nop 0
	v_addc_co_u32_e32 v31, vcc, 0, v29, vcc
	global_load_dwordx4 v[26:29], v[26:27], off
	s_nop 0
	global_load_dwordx4 v[30:33], v[30:31], off
	v_lshlrev_b32_e32 v35, 7, v35
	v_lshlrev_b32_e32 v34, 4, v34
	v_and_or_b32 v194, v34, s55, v35
	v_add_u32_e32 v195, 0x10000, v194
	s_waitcnt vmcnt(7)
	ds_write_b128 v194, v[2:5]
	s_waitcnt vmcnt(6)
	ds_write_b128 v195, v[6:9]
	s_waitcnt vmcnt(5)
	ds_write_b128 v194, v[10:13] offset:8192
	s_waitcnt vmcnt(4)
	ds_write_b128 v195, v[14:17] offset:8192
	s_waitcnt vmcnt(3)
	ds_write_b128 v194, v[18:21] offset:16384
	s_waitcnt vmcnt(2)
	ds_write_b128 v195, v[22:25] offset:16384
	s_waitcnt vmcnt(1)
	ds_write_b128 v194, v[26:29] offset:24576
	s_waitcnt vmcnt(0)
	ds_write_b128 v195, v[30:33] offset:24576
	s_waitcnt lgkmcnt(0)
	s_barrier
	s_and_saveexec_b64 s[10:11], s[2:3]
	s_cbranch_execz .LBB0_1604
	v_add_u32_e32 v2, s4, v172
	v_ashrrev_i32_e32 v3, 31, v2
	v_readlane_b32 s12, v250, 46
	v_lshlrev_b64 v[2:3], 6, v[2:3]
	v_readlane_b32 s13, v250, 47
	s_nop 1
	v_lshl_add_u64 v[14:15], s[12:13], 0, v[2:3]
	global_load_dwordx4 v[2:5], v[14:15], off
	global_load_dwordx4 v[6:9], v[14:15], off offset:16
	global_load_dwordx4 v[10:13], v[14:15], off offset:32
	s_nop 0
	global_load_dwordx4 v[14:17], v[14:15], off offset:48
	s_waitcnt vmcnt(3)
	v_mov_b32_e32 v18, v2
	s_waitcnt vmcnt(2)
	v_mov_b32_e32 v19, v6
	v_mov_b32_e32 v6, v3
	v_mov_b32_e32 v2, v4
	v_mov_b32_e32 v3, v8
	v_mov_b32_e32 v8, v5
	s_waitcnt vmcnt(1)
	v_mov_b32_e32 v4, v10
	s_waitcnt vmcnt(0)
	v_mov_b32_e32 v5, v14
	v_mov_b32_e32 v14, v11
	v_pk_add_f32 v[6:7], v[18:19], v[6:7]
	v_mov_b32_e32 v10, v12
	v_mov_b32_e32 v11, v16
	v_pk_add_f32 v[4:5], v[4:5], v[14:15]
	v_pk_add_f32 v[2:3], v[2:3], v[6:7]
	v_mov_b32_e32 v16, v13
	v_pk_add_f32 v[4:5], v[10:11], v[4:5]
	v_pk_add_f32 v[2:3], v[8:9], v[2:3]
	v_pk_add_f32 v[4:5], v[16:17], v[4:5]
	v_add_f32_e32 v2, v2, v3
	v_add_f32_e32 v2, v2, v4
	v_add_f32_e32 v2, v2, v5
	v_fmamk_f32 v2, v2, 0x3a800000, v206
	v_mul_f32_e32 v3, 0x4b800000, v2
	v_cmp_gt_f32_e32 vcc, s58, v2
	s_nop 1
	v_cndmask_b32_e32 v2, v2, v3, vcc
	v_rsq_f32_e32 v2, v2
	s_nop 0
	v_mul_f32_e32 v3, 0x45800000, v2
	v_cndmask_b32_e32 v2, v2, v3, vcc
	ds_write_b32 v178, v2
